# SB mixer: all 8 K fragments and 16 transposed V reads prefetched from LDS ahead of the MFMA chains; dil mixer: next-next tile V rows loaded straight into their registers instead of temporaries waited
# baseline (speedup 1.0000x reference)
; DI float fexp2(float x) { return __builtin_amdgcn_exp2f(x); }
; DI float flog2(float x) { return __builtin_amdgcn_logf(x); }
; DI float shflx(float v, int mask, int lane) { return __int_as_float(__builtin_amdgcn_ds_bpermute((lane ^ mask) << 2, __float_as_int(v))); }
; DI int crow(int i, int h) { return (i & 3) + 8 * (i >> 2) + 4 * h; }
; #define MFMA32(a, b, c) __builtin_amdgcn_mfma_f32_32x32x16_bf16((a), (b), (c), 0, 0, 0)
; DI s16x4 tr_read(const char* p) { return __builtin_amdgcn_ds_read_tr16_b64_v4i16((LAS s16x4*)p); }
; DI void mix_sb(WVP u16* __restrict__ proj, char* smem) {
;     ...
;         const char* kb_ = kbuf + cur * TB; const char* vb_ = vbuf + cur * TB;
;         f32x16 sacc; for (int i = 0; i < 16; ++i) sacc[i] = 0.f;
;         for (int s = 0; s < 8; ++s) { bf16x8 ak = *(const bf16x8*)(kb_ + l31 * RS + 32 * s + 16 * h); sacc = MFMA32(ak, bq[s], sacc); }
;         const bool diag = (kt == kt_diag);
;         float ls[16];
;         for (int i = 0; i < 16; ++i) {
;           float z2 = sacc[i] * sc;
;           float sp = fmaxf(z2, 0.f) + flog2(1.f + fexp2(-fabsf(z2)));
;           bool ok = !diag || (crow(i, h) < l31);
;           ls[i] = ok ? -sp : 0.f;
;           sacc[i] = ok ? z2 : -1e30f;
;         }
;         float G[4], Gp[4], tot[4];
;         for (int g = 0; g < 4; ++g) G[g] = (ls[4 * g] + ls[4 * g + 1]) + (ls[4 * g + 2] + ls[4 * g + 3]);
;         for (int g = 0; g < 4; ++g) { Gp[g] = shflx(G[g], 32, lane); tot[g] = G[g] + Gp[g]; }
;     ...
;         for (int s = 0; s < 2; ++s) {
;           bf16x8 pf = packP(sacc, s);
;           for (int e = 0; e < 4; ++e) {
;             s16x4 lo = tr_read(vb_ + (16 * s + 4 * h + tq) * RS + e * 64 + 32 * blk + 8 * tp);
;             s16x4 hi = tr_read(vb_ + (16 * s + 8 + 4 * h + tq) * RS + e * 64 + 32 * blk + 8 * tp);
;             bf16x8 av = __builtin_shufflevector(lo, hi, 0, 1, 2, 3, 4, 5, 6, 7);
;             O[e] = MFMA32(av, pf, O[e]);
;           }
;         }
.LBB0_327:
	s_mul_i32 s0, s50, 0x2200
	v_add_u32_e32 v127, s0, v140
	ds_read_b128 v[66:69], v127
	ds_read_b128 v[132:135], v127 offset:32
	ds_read_b128 v[162:165], v127 offset:64
	ds_read_b128 v[166:169], v127 offset:96
	ds_read_b128 v[170:173], v127 offset:128
	ds_read_b128 v[174:177], v127 offset:160
	ds_read_b128 v[178:181], v127 offset:192
	ds_read_b128 v[182:185], v127 offset:224
	s_cmp_lg_u32 s51, s85
	s_cselect_b64 s[66:67], -1, 0
	s_or_b64 vcc, s[66:67], s[14:15]
	s_waitcnt lgkmcnt(7)
	v_mfma_f32_32x32x16_bf16 v[66:81], v[66:69], v[90:93], 0
	v_add_f32_e32 v161, 0, v125
	s_waitcnt lgkmcnt(6)
	v_mfma_f32_32x32x16_bf16 v[66:81], v[132:135], v[94:97], v[66:81]
	s_waitcnt lgkmcnt(5)
	v_mfma_f32_32x32x16_bf16 v[66:81], v[162:165], v[98:101], v[66:81]
	s_waitcnt lgkmcnt(4)
	v_mfma_f32_32x32x16_bf16 v[66:81], v[166:169], v[102:105], v[66:81]
	s_waitcnt lgkmcnt(3)
	v_mfma_f32_32x32x16_bf16 v[66:81], v[170:173], v[106:109], v[66:81]
	s_waitcnt lgkmcnt(2)
	v_mfma_f32_32x32x16_bf16 v[66:81], v[174:177], v[110:113], v[66:81]
	s_waitcnt lgkmcnt(1)
	v_mfma_f32_32x32x16_bf16 v[66:81], v[178:181], v[114:117], v[66:81]
	s_waitcnt lgkmcnt(0)
	v_mfma_f32_32x32x16_bf16 v[66:81], v[182:185], v[118:121], v[66:81]
	v_add_u32_e32 v202, s0, v142
	ds_read_b64_tr_b16 v[186:187], v202 offset:17408
	ds_read_b64_tr_b16 v[188:189], v202 offset:19584
	ds_read_b64_tr_b16 v[190:191], v202 offset:17472
	ds_read_b64_tr_b16 v[192:193], v202 offset:19648
	ds_read_b64_tr_b16 v[194:195], v202 offset:17536
	ds_read_b64_tr_b16 v[196:197], v202 offset:19712
	ds_read_b64_tr_b16 v[198:199], v202 offset:17600
	ds_read_b64_tr_b16 v[200:201], v202 offset:19776
	ds_read_b64_tr_b16 v[206:207], v202 offset:21760
	ds_read_b64_tr_b16 v[208:209], v202 offset:23936
	ds_read_b64_tr_b16 v[210:211], v202 offset:21824
	ds_read_b64_tr_b16 v[212:213], v202 offset:24000
	ds_read_b64_tr_b16 v[214:215], v202 offset:21888
	ds_read_b64_tr_b16 v[216:217], v202 offset:24064
	ds_read_b64_tr_b16 v[218:219], v202 offset:21952
	ds_read_b64_tr_b16 v[220:221], v202 offset:24128
	s_nop 11
	v_mul_f32_e32 v127, 0x3e0293ee, v66
	v_exp_f32_e64 v132, -|v127|
	v_mul_f32_e32 v67, 0x3e0293ee, v67
	v_exp_f32_e64 v133, -|v67|
	v_max_f32_e32 v66, 0, v127
	v_add_f32_e32 v132, 1.0, v132
	v_log_f32_e32 v132, v132
	v_add_f32_e32 v133, 1.0, v133
	v_log_f32_e32 v133, v133
	v_cndmask_b32_e32 v127, v204, v127, vcc
	v_add_f32_e32 v66, v66, v132
	v_cndmask_b32_e64 v66, 0, -v66, vcc
	s_or_b64 vcc, s[66:67], s[16:17]
	v_max_f32_e32 v132, 0, v67
	v_cndmask_b32_e32 v144, v204, v67, vcc
	v_mul_f32_e32 v67, 0x3e0293ee, v68
	v_add_f32_e32 v132, v132, v133
	v_exp_f32_e64 v133, -|v67|
	v_cndmask_b32_e64 v132, 0, -v132, vcc
	s_or_b64 vcc, s[66:67], s[18:19]
	v_max_f32_e32 v68, 0, v67
	v_add_f32_e32 v133, 1.0, v133
	v_log_f32_e32 v133, v133
	v_cndmask_b32_e32 v145, v204, v67, vcc
	v_mul_f32_e32 v67, 0x3e0293ee, v69
	v_max_f32_e32 v69, 0, v67
	v_add_f32_e32 v68, v68, v133
	v_exp_f32_e64 v133, -|v67|
	v_cndmask_b32_e64 v68, 0, -v68, vcc
	s_or_b64 vcc, s[66:67], s[20:21]
	v_cndmask_b32_e32 v146, v204, v67, vcc
	v_mul_f32_e32 v67, 0x3e0293ee, v70
	v_exp_f32_e64 v70, -|v67|
	v_add_f32_e32 v133, 1.0, v133
	v_log_f32_e32 v133, v133
	v_add_f32_e32 v70, 1.0, v70
	v_log_f32_e32 v70, v70
	v_add_f32_e32 v69, v69, v133
	v_cndmask_b32_e64 v134, 0, -v69, vcc
	s_or_b64 vcc, s[66:67], s[22:23]
	v_max_f32_e32 v69, 0, v67
	v_cndmask_b32_e32 v147, v204, v67, vcc
	v_mul_f32_e32 v67, 0x3e0293ee, v71
	v_add_f32_e32 v69, v69, v70
	v_exp_f32_e64 v70, -|v67|
	v_cndmask_b32_e64 v148, 0, -v69, vcc
	s_or_b64 vcc, s[66:67], s[24:25]
	v_max_f32_e32 v69, 0, v67
	v_add_f32_e32 v70, 1.0, v70
	v_log_f32_e32 v70, v70
	v_cndmask_b32_e32 v149, v204, v67, vcc
	v_mul_f32_e32 v67, 0x3e0293ee, v72
	v_add_f32_e32 v69, v69, v70
	v_exp_f32_e64 v70, -|v67|
	v_cndmask_b32_e64 v150, 0, -v69, vcc
	s_or_b64 vcc, s[66:67], s[26:27]
	v_max_f32_e32 v69, 0, v67
	v_add_f32_e32 v70, 1.0, v70
	v_log_f32_e32 v70, v70
	v_cndmask_b32_e32 v72, v204, v67, vcc
	v_mul_f32_e32 v67, 0x3e0293ee, v73
	v_add_f32_e32 v69, v69, v70
	v_exp_f32_e64 v70, -|v67|
	v_cndmask_b32_e64 v151, 0, -v69, vcc
	v_max_f32_e32 v69, 0, v67
	s_or_b64 vcc, s[66:67], s[28:29]
	v_add_f32_e32 v70, 1.0, v70
	v_log_f32_e32 v70, v70
	v_cndmask_b32_e32 v73, v204, v67, vcc
	v_mul_f32_e32 v67, 0x3e0293ee, v74
	v_add_f32_e32 v69, v69, v70
	v_cndmask_b32_e64 v152, 0, -v69, vcc
	v_exp_f32_e64 v70, -|v67|
	s_or_b64 vcc, s[66:67], s[30:31]
	v_max_f32_e32 v69, 0, v67
	v_cndmask_b32_e32 v71, v204, v67, vcc
	v_mul_f32_e32 v67, 0x3e0293ee, v75
	v_exp_f32_e64 v74, -|v67|
	v_add_f32_e32 v70, 1.0, v70
	v_log_f32_e32 v70, v70
	v_add_f32_e32 v74, 1.0, v74
	v_log_f32_e32 v74, v74
	v_add_f32_e32 v69, v69, v70
	v_cndmask_b32_e64 v70, 0, -v69, vcc
	v_max_f32_e32 v69, 0, v67
	s_or_b64 vcc, s[66:67], s[34:35]
	v_add_f32_e32 v69, v69, v74
	v_cndmask_b32_e32 v75, v204, v67, vcc
	v_mul_f32_e32 v67, 0x3e0293ee, v76
	v_cndmask_b32_e64 v74, 0, -v69, vcc
	v_exp_f32_e64 v76, -|v67|
	s_or_b64 vcc, s[66:67], s[36:37]
	v_max_f32_e32 v69, 0, v67
	v_cndmask_b32_e32 v153, v204, v67, vcc
	v_mul_f32_e32 v67, 0x3e0293ee, v77
	v_exp_f32_e64 v77, -|v67|
	v_add_f32_e32 v76, 1.0, v76
	v_log_f32_e32 v76, v76
	v_add_f32_e32 v77, 1.0, v77
	v_log_f32_e32 v77, v77
	v_add_f32_e32 v69, v69, v76
	v_cndmask_b32_e64 v76, 0, -v69, vcc
	v_max_f32_e32 v69, 0, v67
	s_or_b64 vcc, s[66:67], s[38:39]
	v_add_f32_e32 v69, v69, v77
	v_cndmask_b32_e32 v154, v204, v67, vcc
	v_mul_f32_e32 v67, 0x3e0293ee, v78
	v_cndmask_b32_e64 v77, 0, -v69, vcc
	v_exp_f32_e64 v78, -|v67|
	s_or_b64 vcc, s[66:67], s[40:41]
	v_max_f32_e32 v69, 0, v67
	v_cndmask_b32_e32 v135, v204, v67, vcc
	v_mul_f32_e32 v67, 0x3e0293ee, v79
	v_exp_f32_e64 v79, -|v67|
	v_add_f32_e32 v78, 1.0, v78
	v_log_f32_e32 v78, v78
	v_add_f32_e32 v133, v76, v77
	v_add_f32_e32 v79, 1.0, v79
	v_log_f32_e32 v79, v79
	v_add_f32_e32 v69, v69, v78
	v_cndmask_b32_e64 v78, 0, -v69, vcc
	v_max_f32_e32 v69, 0, v67
	s_or_b64 vcc, s[66:67], s[42:43]
	v_add_f32_e32 v69, v69, v79
	v_cndmask_b32_e32 v155, v204, v67, vcc
	v_mul_f32_e32 v67, 0x3e0293ee, v80
	v_cndmask_b32_e64 v79, 0, -v69, vcc
	v_exp_f32_e64 v80, -|v67|
	s_or_b64 vcc, s[66:67], s[44:45]
	v_max_f32_e32 v69, 0, v67
	v_cndmask_b32_e32 v156, v204, v67, vcc
	v_mul_f32_e32 v67, 0x3e0293ee, v81
	v_exp_f32_e64 v81, -|v67|
	v_add_f32_e32 v80, 1.0, v80
	v_log_f32_e32 v80, v80
	v_add_f32_e32 v81, 1.0, v81
	v_log_f32_e32 v81, v81
	v_add_f32_e32 v69, v69, v80
	v_cndmask_b32_e64 v80, 0, -v69, vcc
	v_max_f32_e32 v69, 0, v67
	v_add_f32_e32 v69, v69, v81
	s_or_b64 vcc, s[66:67], s[46:47]
	v_cndmask_b32_e64 v81, 0, -v69, vcc
	v_cndmask_b32_e32 v157, v204, v67, vcc
	v_add_f32_e32 v67, v148, v150
	v_add_f32_e32 v69, v151, v152
	v_add_f32_e32 v67, v67, v69
	v_add_f32_e32 v69, v70, v74
	v_add_f32_e32 v69, v69, v133
	v_add_f32_e32 v133, v78, v79
	v_add_f32_e32 v158, v80, v81
	v_add_f32_e32 v158, v133, v158
	ds_bpermute_b32 v160, v141, v158
	ds_bpermute_b32 v159, v141, v69
	ds_bpermute_b32 v133, v141, v67
	s_waitcnt lgkmcnt(2)
; DI float fexp2(float x) { return __builtin_amdgcn_exp2f(x); }
; DI float shflx(float v, int mask, int lane) { return __int_as_float(__builtin_amdgcn_ds_bpermute((lane ^ mask) << 2, __float_as_int(v))); }
; #define MFMA32(a, b, c) __builtin_amdgcn_mfma_f32_32x32x16_bf16((a), (b), (c), 0, 0, 0)
; DI s16x4 tr_read(const char* p) { return __builtin_amdgcn_ds_read_tr16_b64_v4i16((LAS s16x4*)p); }
; DI void mix_sb(WVP u16* __restrict__ proj, char* smem) {
;     ...
;         for (int g = 0; g < 4; ++g) { Gp[g] = shflx(G[g], 32, lane); tot[g] = G[g] + Gp[g]; }
;         float after = 0.f;
;         for (int g = 3; g >= 0; --g) {
;           float tail = R + after + (h == 0 ? Gp[g] : 0.f);
;           float c3 = tail + ls[4 * g + 3], c2 = c3 + ls[4 * g + 2], c1 = c2 + ls[4 * g + 1], c0 = c1 + ls[4 * g];
;           sacc[4 * g + 3] = fexp2(sacc[4 * g + 3] + c3); sacc[4 * g + 2] = fexp2(sacc[4 * g + 2] + c2);
;           sacc[4 * g + 1] = fexp2(sacc[4 * g + 1] + c1); sacc[4 * g] = fexp2(sacc[4 * g] + c0);
;           after += tot[g];
;         }
;         R += after;
;         for (int s = 0; s < 2; ++s) {
;           bf16x8 pf = packP(sacc, s);
;           for (int e = 0; e < 4; ++e) {
;             s16x4 lo = tr_read(vb_ + (16 * s + 4 * h + tq) * RS + e * 64 + 32 * blk + 8 * tp);
;             s16x4 hi = tr_read(vb_ + (16 * s + 8 + 4 * h + tq) * RS + e * 64 + 32 * blk + 8 * tp);
;             bf16x8 av = __builtin_shufflevector(lo, hi, 0, 1, 2, 3, 4, 5, 6, 7);
;             O[e] = MFMA32(av, pf, O[e]);
;           }
;         }
;         wdone = __all(R < RTH);
	v_add_f32_e32 v158, v158, v160
	v_cndmask_b32_e64 v160, 0, v160, s[10:11]
	v_add_f32_e32 v160, v161, v160
	v_add_f32_e32 v81, v160, v81
	v_add_f32_e32 v80, v80, v81
	v_add_f32_e32 v79, v79, v80
	v_add_f32_e32 v78, v78, v79
	v_add_f32_e32 v78, v135, v78
	v_add_f32_e32 v135, 0, v158
	v_add_f32_e32 v80, v156, v80
	v_add_f32_e32 v79, v155, v79
	v_add_f32_e32 v155, v125, v135
	s_waitcnt lgkmcnt(1)
	v_cndmask_b32_e64 v156, 0, v159, s[10:11]
	v_add_f32_e32 v155, v156, v155
	v_add_f32_e32 v77, v77, v155
	v_add_f32_e32 v76, v76, v77
	v_add_f32_e32 v74, v74, v76
	v_add_f32_e32 v70, v70, v74
	v_add_f32_e32 v69, v69, v159
	v_add_f32_e32 v74, v75, v74
	v_add_f32_e32 v70, v71, v70
	v_add_f32_e32 v77, v154, v77
	v_add_f32_e32 v76, v153, v76
	v_exp_f32_e32 v153, v74
	v_exp_f32_e32 v154, v70
	s_waitcnt lgkmcnt(0)
	v_pk_add_f32 v[70:71], v[66:67], v[132:133]
	v_pk_add_f32 v[74:75], v[68:69], v[134:135]
	v_cndmask_b32_e64 v155, 0, v133, s[10:11]
	v_pk_add_f32 v[70:71], v[70:71], v[74:75]
	ds_bpermute_b32 v67, v141, v70
	v_add_f32_e32 v69, v125, v75
	v_add_f32_e32 v69, v155, v69
	v_add_f32_e32 v69, v152, v69
	v_add_f32_e32 v74, v151, v69
	v_add_f32_e32 v75, v150, v74
	s_waitcnt lgkmcnt(0)
	v_add_f32_e32 v70, v70, v67
	v_add_f32_e32 v133, v148, v75
	v_add_f32_e32 v69, v73, v69
	v_add_f32_e32 v73, v149, v75
	v_add_f32_e32 v75, v125, v71
	v_cndmask_b32_e64 v67, 0, v67, s[10:11]
	v_add_f32_e32 v67, v67, v75
	v_add_f32_e32 v67, v134, v67
	v_add_f32_e32 v68, v68, v67
	v_add_f32_e32 v75, v132, v68
	v_add_f32_e32 v66, v66, v75
	v_add_f32_e32 v72, v72, v74
	v_add_f32_e32 v74, v147, v133
	v_add_f32_e32 v67, v146, v67
	v_add_f32_e32 v68, v145, v68
	v_add_f32_e32 v75, v144, v75
	v_add_f32_e32 v66, v127, v66
	v_exp_f32_e32 v69, v69
	v_exp_f32_e32 v72, v72
	v_exp_f32_e32 v73, v73
	v_exp_f32_e32 v74, v74
	v_exp_f32_e32 v67, v67
	v_exp_f32_e32 v68, v68
	v_exp_f32_e32 v75, v75
	v_exp_f32_e32 v66, v66
	v_add_u32_e32 v127, s0, v142
	v_cvt_pk_bf16_f32 v67, v68, v67
	v_cvt_pk_bf16_f32 v68, v74, v73
	v_cvt_pk_bf16_f32 v66, v66, v75
	v_cvt_pk_bf16_f32 v69, v72, v69
	s_waitcnt lgkmcnt(0)
	v_mfma_f32_32x32x16_bf16 v[34:49], v[186:189], v[66:69], v[34:49]
	v_add_f32_e32 v81, v157, v81
	v_exp_f32_e32 v81, v81
	v_exp_f32_e32 v80, v80
	v_exp_f32_e32 v79, v79
	v_exp_f32_e32 v78, v78
	v_exp_f32_e32 v77, v77
	s_waitcnt lgkmcnt(0)
	v_mfma_f32_32x32x16_bf16 v[50:65], v[190:193], v[66:69], v[50:65]
	v_exp_f32_e32 v76, v76
	s_mov_b32 s0, 0xc2700000
	s_waitcnt lgkmcnt(0)
	v_mfma_f32_32x32x16_bf16 v[18:33], v[194:197], v[66:69], v[18:33]
	s_waitcnt lgkmcnt(0)
	v_mfma_f32_32x32x16_bf16 v[2:17], v[198:201], v[66:69], v[2:17]
	v_cvt_pk_bf16_f32 v66, v154, v153
	v_cvt_pk_bf16_f32 v67, v76, v77
	v_cvt_pk_bf16_f32 v68, v78, v79
	v_cvt_pk_bf16_f32 v69, v80, v81
	s_waitcnt lgkmcnt(0)
	s_nop 0
	v_mfma_f32_32x32x16_bf16 v[34:49], v[206:209], v[66:69], v[34:49]
	s_waitcnt lgkmcnt(0)
	v_mfma_f32_32x32x16_bf16 v[50:65], v[210:213], v[66:69], v[50:65]
	s_waitcnt lgkmcnt(0)
	v_mfma_f32_32x32x16_bf16 v[18:33], v[214:217], v[66:69], v[18:33]
	s_waitcnt lgkmcnt(0)
	v_mfma_f32_32x32x16_bf16 v[2:17], v[218:221], v[66:69], v[2:17]
	v_add_f32_e32 v66, v70, v71
	v_add_f32_e32 v125, v125, v66
	v_cmp_gt_f32_e32 vcc, s0, v125
	s_cmp_eq_u64 vcc, exec
	s_cselect_b64 s[0:1], -1, 0
	v_cndmask_b32_e64 v66, 0, 1, s[0:1]
	s_and_saveexec_b64 s[66:67], s[12:13]
	s_cbranch_execz .LBB0_323

; #define MFMA32(a, b, c) __builtin_amdgcn_mfma_f32_32x32x16_bf16((a), (b), (c), 0, 0, 0)
; DI void mix_dil(WVP u16* __restrict__ proj, float* __restrict__ lse, const float* __restrict__ rel_bias, char* smem) {
;     ...
;     for (int j = j0; j < 5; ++j) {
;       const int kb = q0 - 128 + 32 * j;
;       for (int c = 0; c < 4; ++c) *(u32x4*)(vbuf + l31 * 144 + h * 64 + c * 16) = vv[c];
;       f32x16 snx; for (int i = 0; i < 16; ++i) snx[i] = 0.f;
;       if (j + 1 < 5) {
;         for (int s = 0; s < 4; ++s) snx = MFMA32(ak_n[s], bq[s], snx);
;         for (int c = 0; c < 4; ++c) vv[c] = vv_n[c];
;         if (j + 2 < 5) {
;           const u16* kp = kbase_ + (long)(kb + 64 + l31) * dil * INW;
;           for (int s = 0; s < 4; ++s) ak_n[s] = *(const bf16x8*)(kp + 16 * s + 8 * h);
;           for (int c = 0; c < 4; ++c) vv_n[c] = *(const u32x4*)(kp + 768 + h * 32 + c * 8);
;         }
.LBB0_341:
	s_cmp_eq_u32 s11, 4
	ds_write_b128 v211, v[136:139] offset:6336
	ds_write_b128 v211, v[140:143] offset:6352
	ds_write_b128 v211, v[132:135] offset:6368
	ds_write_b128 v211, v[128:131] offset:6384
	s_cbranch_scc1 .LBB0_345
	s_waitcnt vmcnt(7)
	v_mfma_f32_32x32x16_bf16 v[64:79], v[80:83], v[96:99], 0
	s_waitcnt vmcnt(0)
	v_mov_b64_e32 v[130:131], v[114:115]
	v_mov_b64_e32 v[134:135], v[118:119]
	s_cmp_gt_i32 s11, 2
	v_mov_b64_e32 v[142:143], v[126:127]
	v_mov_b64_e32 v[138:139], v[122:123]
	v_mfma_f32_32x32x16_bf16 v[64:79], v[84:87], v[100:103], v[64:79]
	v_mov_b64_e32 v[128:129], v[112:113]
	v_mov_b64_e32 v[132:133], v[116:117]
	v_mfma_f32_32x32x16_bf16 v[64:79], v[88:91], v[104:107], v[64:79]
	v_mov_b64_e32 v[140:141], v[124:125]
	v_mov_b64_e32 v[136:137], v[120:121]
	v_mfma_f32_32x32x16_bf16 v[64:79], v[92:95], v[108:111], v[64:79]
	s_cbranch_scc1 .LBB0_344
	v_lshlrev_b64 v[2:3], s0, v[192:193]
	v_mov_b64_e32 v[4:5], s[16:17]
	v_mad_u64_u32 v[4:5], s[20:21], v2, s86, v[4:5]
	v_mov_b32_e32 v0, v5
	v_mad_u64_u32 v[2:3], s[20:21], v3, s86, v[0:1]
	v_mov_b32_e32 v5, v2
	v_mov_b32_e32 v181, v1
	v_lshl_add_u64 v[2:3], v[4:5], 0, v[180:181]
	v_mov_b32_e32 v183, v1
	global_load_dwordx4 v[80:83], v[2:3], off offset:2560
	global_load_dwordx4 v[84:87], v[2:3], off offset:2592
	global_load_dwordx4 v[88:91], v[2:3], off offset:2624
	global_load_dwordx4 v[92:95], v[2:3], off offset:2656
	v_lshl_add_u64 v[2:3], v[4:5], 0, v[182:183]
	s_mov_b64 s[20:21], 0x1000
	v_lshl_add_u64 v[6:7], v[2:3], 0, s[20:21]
	v_add_co_u32_e32 v2, vcc, s47, v2
	s_nop 1
	v_addc_co_u32_e32 v3, vcc, 0, v3, vcc
	global_load_dwordx4 v[120:123], v[2:3], off
	s_nop 0
	global_load_dwordx4 v[112:115], v[6:7], off offset:48
	global_load_dwordx4 v[116:119], v[6:7], off offset:32
	s_nop 0
	global_load_dwordx4 v[124:127], v[6:7], off offset:16
.LBB0_344:
	s_branch .LBB0_347
.LBB0_345:
	v_mov_b32_e32 v14, v1
	v_mov_b32_e32 v15, v1
	v_mov_b32_e32 v0, v1
	v_mov_b32_e32 v2, v1
	v_mov_b32_e32 v3, v1
	v_mov_b32_e32 v4, v1
	v_mov_b32_e32 v5, v1
	v_mov_b32_e32 v6, v1
	v_mov_b32_e32 v7, v1
	v_mov_b32_e32 v8, v1
	v_mov_b32_e32 v9, v1
	v_mov_b32_e32 v10, v1
	v_mov_b32_e32 v11, v1
	v_mov_b32_e32 v12, v1
	v_mov_b32_e32 v13, v1
	v_mov_b64_e32 v[78:79], v[14:15]
	s_mov_b64 s[20:21], s[18:19]
	v_mov_b64_e32 v[76:77], v[12:13]
	v_mov_b64_e32 v[74:75], v[10:11]
	v_mov_b64_e32 v[72:73], v[8:9]
	v_mov_b64_e32 v[70:71], v[6:7]
	v_mov_b64_e32 v[68:69], v[4:5]
	v_mov_b64_e32 v[66:67], v[2:3]
	v_mov_b64_e32 v[64:65], v[0:1]
	s_and_b64 vcc, exec, s[20:21]
	s_cbranch_vccnz .LBB0_347
